# ssm pass2 group loop rewritten by hand: transposed Bu tile (b128 scan reads), packed bf16 state tile, scalar fmac scan, ud via identity MFMA
# speedup vs baseline: 1.0091x; 1.0091x over previous
; __device__ __forceinline__ void ssm_pass2(LAS unsigned char* lds, const bf16_t* US, const float* SST, bf16_t* YB, const float* ABAR, const bf16_t* BBH, const bf16_t* BBL, const bf16_t* CMH, const bf16_t* CML, const float* dco, int gw, int NGW, int lane, int wave) {
;     ...
;         for (int ks = 0; ks < 4; ++ks) { const size_t o = (size_t)(g * 16 + fr) * 128 + ks * 32 + fq * 8; ch[ks] = *(const bf16x8*)(CMH + o); }
;         const float dh = dco[g * 16 + fr];
;         float pr = S.ar, pi = S.ai;
; #pragma unroll
;         for (int s = 0; s < 8; ++s) { const float nr = pr * pr - pi * pi, ni = 2.f * pr * pi; pr = nr; pi = ni; }
;         float xr = 0.f, xi = 0.f;
;         { float sr[7], sm[7];
; #pragma unroll
;           for (int cc = 0; cc < 7; ++cc) { const float* si = SST + ((size_t)bg * 8 + (cc < c ? cc : 0)) * 128; sr[cc] = si[lane]; sm[cc] = si[64 + lane]; }
; #pragma unroll
;           for (int cc = 0; cc < 7; ++cc) if (cc < c) { const float nr = pr * xr - pi * xi + sr[cc], ni = pr * xi + pi * xr + sm[cc]; xr = nr; xi = ni; } }
;         const int tokc = b * SEQ + c * 256;
;         bf16x8 uh; ssm_u_load(uh, US, tokc, g, lane);
.LBB0_549:
	s_and_b32 s21, s68, 0xfffff800
	v_or_b32_e32 v125, s21, v120
	v_or_b32_e32 v126, s21, v121
	s_lshl_b32 s21, s70, 3
	v_mul_f32_e32 v48, v66, v52
	s_and_b32 s21, s21, 0xfffff800
	v_fma_f32 v48, v65, v53, -v48
	s_or_b32 s59, s21, s3
	v_add_f32_e32 v68, v50, v48
	v_or_b32_e32 v48, s59, v114
	v_ashrrev_i32_e32 v49, 31, v48
	v_lshlrev_b64 v[48:49], 10, v[48:49]
	v_lshl_add_u64 v[48:49], s[46:47], 0, v[48:49]
	s_lshl_b32 s20, s20, 1
	s_mov_b32 s21, s57
	v_lshl_add_u64 v[48:49], v[48:49], 0, s[20:21]
	v_lshl_add_u64 v[48:49], v[48:49], 0, v[80:81]
	global_load_dwordx4 v[48:51], v[48:49], off
	v_mul_f32_e32 v67, v66, v53
	v_fmac_f32_e32 v67, v65, v52
	v_add_f32_e32 v64, v64, v67
	v_cndmask_b32_e64 v52, v52, v64, s[8:9]
	v_cndmask_b32_e64 v53, v53, v68, s[8:9]
	v_mul_f32_e32 v64, v66, v53
	v_mul_f32_e32 v67, v66, v52
	v_fmac_f32_e32 v64, v65, v52
	v_fma_f32 v67, v65, v53, -v67
	v_add_f32_e32 v62, v62, v67
	v_add_f32_e32 v63, v63, v64
	v_cndmask_b32_e64 v52, v52, v63, s[10:11]
	v_cndmask_b32_e64 v53, v53, v62, s[10:11]
	v_mul_f32_e32 v62, v66, v53
	v_mul_f32_e32 v63, v66, v52
	v_fmac_f32_e32 v62, v65, v52
	v_fma_f32 v63, v65, v53, -v63
	v_add_f32_e32 v60, v60, v63
	v_add_f32_e32 v61, v61, v62
	v_cndmask_b32_e64 v52, v52, v61, s[12:13]
	v_cndmask_b32_e64 v53, v53, v60, s[12:13]
	v_mul_f32_e32 v60, v66, v53
	v_mul_f32_e32 v61, v66, v52
	v_fmac_f32_e32 v60, v65, v52
	v_fma_f32 v61, v65, v53, -v61
	v_add_f32_e32 v56, v56, v61
	v_add_f32_e32 v57, v57, v60
	v_cndmask_b32_e64 v52, v52, v57, s[14:15]
	v_cndmask_b32_e64 v53, v53, v56, s[14:15]
	v_mul_f32_e32 v56, v66, v53
	v_mul_f32_e32 v57, v66, v52
	v_fmac_f32_e32 v56, v65, v52
	v_fma_f32 v57, v65, v53, -v57
	v_add_f32_e32 v57, v58, v57
	v_add_f32_e32 v56, v59, v56
	v_cndmask_b32_e64 v52, v52, v56, s[16:17]
	v_cndmask_b32_e64 v53, v53, v57, s[16:17]
	v_mul_f32_e32 v56, v66, v53
	v_mul_f32_e32 v57, v66, v52
	v_fmac_f32_e32 v56, v65, v52
	v_fma_f32 v57, v65, v53, -v57
	v_add_f32_e32 v54, v54, v57
	v_add_f32_e32 v55, v55, v56
	v_pk_mov_b32 v[94:95], v[90:91], v[90:91] op_sel:[1,0]
	v_cndmask_b32_e64 v76, v52, v55, s[18:19]
	v_cndmask_b32_e64 v100, v53, v54, s[18:19]
	v_cndmask_b32_e64 v19, 0, v19, s[4:5]
	v_cndmask_b32_e64 v18, 0, v18, s[4:5]
	v_cndmask_b32_e64 v17, 0, v17, s[4:5]
	v_cndmask_b32_e64 v16, 0, v16, s[4:5]
	v_cndmask_b32_e64 v23, 0, v23, s[4:5]
	v_cndmask_b32_e64 v22, 0, v22, s[4:5]
	v_cndmask_b32_e64 v21, 0, v21, s[4:5]
	v_cndmask_b32_e64 v20, 0, v20, s[4:5]
	v_cndmask_b32_e64 v27, 0, v27, s[4:5]
	v_cndmask_b32_e64 v26, 0, v26, s[4:5]
	v_cndmask_b32_e64 v25, 0, v25, s[4:5]
	v_cndmask_b32_e64 v24, 0, v24, s[4:5]
	v_cndmask_b32_e64 v31, 0, v31, s[4:5]
	v_cndmask_b32_e64 v30, 0, v30, s[4:5]
	v_cndmask_b32_e64 v29, 0, v29, s[4:5]
	v_cndmask_b32_e64 v28, 0, v28, s[4:5]
	v_cndmask_b32_e64 v35, 0, v35, s[4:5]
	v_cndmask_b32_e64 v34, 0, v34, s[4:5]
	v_cndmask_b32_e64 v33, 0, v33, s[4:5]
	v_cndmask_b32_e64 v32, 0, v32, s[4:5]
	v_cndmask_b32_e64 v39, 0, v39, s[4:5]
	v_cndmask_b32_e64 v38, 0, v38, s[4:5]
	v_cndmask_b32_e64 v37, 0, v37, s[4:5]
	v_cndmask_b32_e64 v36, 0, v36, s[4:5]
	v_cndmask_b32_e64 v43, 0, v43, s[4:5]
	v_cndmask_b32_e64 v42, 0, v42, s[4:5]
	v_cndmask_b32_e64 v41, 0, v41, s[4:5]
	v_cndmask_b32_e64 v40, 0, v40, s[4:5]
	v_cndmask_b32_e64 v47, 0, v47, s[4:5]
	v_cndmask_b32_e64 v46, 0, v46, s[4:5]
	v_cndmask_b32_e64 v45, 0, v45, s[4:5]
	v_cndmask_b32_e64 v44, 0, v44, s[4:5]
	v_lshl_add_u64 v[98:99], v[84:85], 0, s[20:21]
	v_lshl_add_u64 v[96:97], v[86:87], 0, s[20:21]
	v_lshl_add_u64 v[92:93], v[88:89], 0, s[20:21]
	v_readlane_b32 s98, v249, 18
	s_mov_b32 s100, 0x4000
	s_mov_b32 s101, 0
	s_lshl_b32 s99, s20, 7
	s_mul_i32 s98, s98, 0x3a00
	v_lshrrev_b32_e32 v109, 4, v196
	v_mul_u32_u24_e32 v144, 0x50, v114
	v_lshl_add_u32 v144, v109, 4, v144
	v_add_u32_e32 v144, s98, v144
	v_mul_u32_u24_e32 v145, 0x50, v196
	v_add_u32_e32 v145, s98, v145
	v_lshl_add_u32 v146, v196, 2, s98
	v_add_u32_e32 v146, 0x2800, v146
	v_mul_u32_u24_e32 v147, 0x120, v114
	v_lshl_add_u32 v147, v109, 4, v147
	v_add_u32_e32 v147, s98, v147
	v_add_u32_e32 v147, 0x2800, v147
	v_xor_b32_e32 v77, 0x80000000, v91
	v_lshlrev_b32_e32 v110, 8, v114
	v_lshl_add_u32 v110, v109, 3, v110
	v_add_u32_e32 v110, s99, v110
	global_load_dwordx2 v[230:231], v110, s[54:55] offset:0
	global_load_dwordx2 v[232:233], v110, s[54:55] offset:128
	global_load_dwordx2 v[234:235], v110, s[54:55] offset:32
	global_load_dwordx2 v[236:237], v110, s[54:55] offset:160
	global_load_dwordx2 v[238:239], v110, s[54:55] offset:64
	global_load_dwordx2 v[240:241], v110, s[54:55] offset:192
	global_load_dwordx2 v[242:243], v110, s[54:55] offset:96
	global_load_dwordx2 v[244:245], v110, s[54:55] offset:224
	v_add_u32_e32 v108, s59, v114
	v_add_u32_e32 v108, 16, v108
	v_lshlrev_b32_e32 v108, 10, v108
	v_mov_b32_e32 v109, 0
	v_lshl_add_u64 v[148:149], v[98:99], 0, v[108:109]
	v_lshrrev_b32_e32 v108, 4, v196
	v_lshl_add_u32 v108, v108, 2, s59
	v_lshlrev_b32_e32 v108, 10, v108
	v_lshl_add_u64 v[150:151], v[92:93], 0, v[108:109]
	s_mov_b32 s99, 0xffff0000
	s_mov_b32 s20, 0
	s_waitcnt vmcnt(0)
	v_and_b32_e32 v101, 0xffff, v230
	v_lshrrev_b32_e32 v102, 16, v230
	v_and_b32_e32 v103, 0xffff, v231
	v_lshrrev_b32_e32 v104, 16, v231
	v_lshl_or_b32 v214, v232, 16, v101
	v_and_or_b32 v215, v232, s99, v102
	v_lshl_or_b32 v216, v233, 16, v103
	v_and_or_b32 v217, v233, s99, v104
	v_and_b32_e32 v101, 0xffff, v234
	v_lshrrev_b32_e32 v102, 16, v234
	v_and_b32_e32 v103, 0xffff, v235
	v_lshrrev_b32_e32 v104, 16, v235
	v_lshl_or_b32 v218, v236, 16, v101
	v_and_or_b32 v219, v236, s99, v102
	v_lshl_or_b32 v220, v237, 16, v103
	v_and_or_b32 v221, v237, s99, v104
	v_and_b32_e32 v101, 0xffff, v238
	v_lshrrev_b32_e32 v102, 16, v238
	v_and_b32_e32 v103, 0xffff, v239
	v_lshrrev_b32_e32 v104, 16, v239
	v_lshl_or_b32 v222, v240, 16, v101
	v_and_or_b32 v223, v240, s99, v102
	v_lshl_or_b32 v224, v241, 16, v103
	v_and_or_b32 v225, v241, s99, v104
	v_and_b32_e32 v101, 0xffff, v242
	v_lshrrev_b32_e32 v102, 16, v242
	v_and_b32_e32 v103, 0xffff, v243
	v_lshrrev_b32_e32 v104, 16, v243
	v_lshl_or_b32 v226, v244, 16, v101
	v_and_or_b32 v227, v244, s99, v102
	v_lshl_or_b32 v228, v245, 16, v103
	v_and_or_b32 v229, v245, s99, v104
; #define LAS __attribute__((address_space(3)))
; __device__ __forceinline__ void ssm_bu_tile(const SsmOps& S, bf16x8 uh, LAS float* tile, int lane) {
;     const int fr = lane & 15, fq = lane >> 4;
;     if (fq >= 2) uh = (bf16x8){0, 0, 0, 0, 0, 0, 0, 0};
; #pragma unroll
;     for (int nb = 0; nb < 8; ++nb) { f32x4 acc = {0.f, 0.f, 0.f, 0.f};
;         acc = __builtin_amdgcn_mfma_f32_16x16x32_bf16(S.bh[nb], uh, acc, 0, 0, 0);
;         *(LAS f32x4*)(tile + fr * TSTR + 16 * nb + 4 * fq) = acc; }
;     asm volatile("s_waitcnt lgkmcnt(0)" ::: "memory");
; }
; __device__ __forceinline__ void ssm_pass2(LAS unsigned char* lds, const bf16_t* US, const float* SST, bf16_t* YB, const float* ABAR, const bf16_t* BBH, const bf16_t* BBL, const bf16_t* CMH, const bf16_t* CML, const float* dco, int gw, int NGW, int lane, int wave) {
;     ...
;         for (int grp = 0; grp < 16; ++grp) { const int tok = tokc + grp * 16;
;             ssm_bu_tile(S, uh, tile, lane);
;             if (grp < 15) ssm_u_load(uh, US, tok + 16, g, lane);
;             float ud[4];
; #pragma unroll
;             for (int i = 0; i < 4; ++i) ud[i] = bf_lo((unsigned)US[(size_t)(tok + 4 * fq + i) * SSMW + g * 16 + fr]);
;             float br[16], bi[16];
; #pragma unroll
;             for (int t = 0; t < 16; ++t) { br[t] = tile[t * TSTR + lane]; bi[t] = tile[t * TSTR + 64 + lane]; }
;             asm volatile("s_waitcnt lgkmcnt(0)" ::: "memory");
; #pragma unroll
;             for (int t = 0; t < 16; ++t) { const float nr = S.ar * xr - S.ai * xi + br[t], ni = S.ar * xi + S.ai * xr + bi[t]; xr = nr; xi = ni; br[t] = xr; bi[t] = xi; }
; #pragma unroll
;             for (int t = 0; t < 16; ++t) { tile[t * TSTR + lane] = br[t]; tile[t * TSTR + 64 + lane] = bi[t]; }
.Lssm2_grp:
	v_cndmask_b32_e64 v55, v51, 0, s[6:7]
	v_cndmask_b32_e64 v54, v50, 0, s[6:7]
	v_cndmask_b32_e64 v53, v49, 0, s[6:7]
	v_cndmask_b32_e64 v52, v48, 0, s[6:7]
	global_load_dwordx4 v[48:51], v[148:149], off
	v_lshl_add_u64 v[148:149], v[148:149], 0, s[100:101]
	v_mfma_f32_16x16x32_bf16 v[160:163], v[52:55], v[16:19], 0
	v_mfma_f32_16x16x32_bf16 v[164:167], v[52:55], v[20:23], 0
	v_mfma_f32_16x16x32_bf16 v[168:171], v[52:55], v[24:27], 0
	v_mfma_f32_16x16x32_bf16 v[172:175], v[52:55], v[28:31], 0
	v_mfma_f32_16x16x32_bf16 v[176:179], v[52:55], v[32:35], 0
	v_mfma_f32_16x16x32_bf16 v[180:183], v[52:55], v[36:39], 0
	v_mfma_f32_16x16x32_bf16 v[184:187], v[52:55], v[40:43], 0
	v_mfma_f32_16x16x32_bf16 v[188:191], v[52:55], v[44:47], 0
	v_mfma_f32_16x16x32_bf16 v[156:159], v[52:55], v[152:155], 0
	ds_write_b128 v144, v[160:163]
	ds_write_b128 v144, v[164:167] offset:1280
	ds_write_b128 v144, v[168:171] offset:2560
	ds_write_b128 v144, v[172:175] offset:3840
	ds_write_b128 v144, v[176:179] offset:5120
	ds_write_b128 v144, v[180:183] offset:6400
	ds_write_b128 v144, v[184:187] offset:7680
	ds_write_b128 v144, v[188:191] offset:8960
	s_waitcnt lgkmcnt(0)
	ds_read_b128 v[0:3], v145
	ds_read_b128 v[60:63], v145 offset:5120
	ds_read_b128 v[4:7], v145 offset:16
	ds_read_b128 v[64:67], v145 offset:5136
	ds_read_b128 v[8:11], v145 offset:32
	ds_read_b128 v[68:71], v145 offset:5152
	ds_read_b128 v[12:15], v145 offset:48
	ds_read_b128 v[72:75], v145 offset:5168
	s_waitcnt lgkmcnt(6)
	v_fmac_f32_e32 v0, v90, v100
	v_fmac_f32_e32 v60, v90, v76
	v_fmac_f32_e32 v0, v77, v76
	v_fmac_f32_e32 v60, v91, v100
	v_fmac_f32_e32 v1, v90, v0
	v_fmac_f32_e32 v61, v90, v60
	v_fmac_f32_e32 v1, v77, v60
	v_fmac_f32_e32 v61, v91, v0
	v_cvt_pk_bf16_f32 v128, v0, v60
	ds_write_b32 v146, v128
	v_fmac_f32_e32 v2, v90, v1
	v_fmac_f32_e32 v62, v90, v61
	v_fmac_f32_e32 v2, v77, v61
	v_fmac_f32_e32 v62, v91, v1
	v_cvt_pk_bf16_f32 v129, v1, v61
	ds_write_b32 v146, v129 offset:288
	v_fmac_f32_e32 v3, v90, v2
	v_fmac_f32_e32 v63, v90, v62
	v_fmac_f32_e32 v3, v77, v62
	v_fmac_f32_e32 v63, v91, v2
	v_cvt_pk_bf16_f32 v130, v2, v62
	ds_write_b32 v146, v130 offset:576
	s_waitcnt lgkmcnt(7)
	v_fmac_f32_e32 v4, v90, v3
	v_fmac_f32_e32 v64, v90, v63
	v_fmac_f32_e32 v4, v77, v63
	v_fmac_f32_e32 v64, v91, v3
	v_cvt_pk_bf16_f32 v131, v3, v63
	ds_write_b32 v146, v131 offset:864
	v_fmac_f32_e32 v5, v90, v4
	v_fmac_f32_e32 v65, v90, v64
	v_fmac_f32_e32 v5, v77, v64
	v_fmac_f32_e32 v65, v91, v4
	v_cvt_pk_bf16_f32 v132, v4, v64
	ds_write_b32 v146, v132 offset:1152
	v_fmac_f32_e32 v6, v90, v5
	v_fmac_f32_e32 v66, v90, v65
	v_fmac_f32_e32 v6, v77, v65
	v_fmac_f32_e32 v66, v91, v5
	v_cvt_pk_bf16_f32 v133, v5, v65
	ds_write_b32 v146, v133 offset:1440
	v_fmac_f32_e32 v7, v90, v6
	v_fmac_f32_e32 v67, v90, v66
	v_fmac_f32_e32 v7, v77, v66
	v_fmac_f32_e32 v67, v91, v6
	v_cvt_pk_bf16_f32 v134, v6, v66
	ds_write_b32 v146, v134 offset:1728
	s_waitcnt lgkmcnt(9)
	v_fmac_f32_e32 v8, v90, v7
	v_fmac_f32_e32 v68, v90, v67
	v_fmac_f32_e32 v8, v77, v67
	v_fmac_f32_e32 v68, v91, v7
	v_cvt_pk_bf16_f32 v135, v7, v67
	ds_write_b32 v146, v135 offset:2016
	v_fmac_f32_e32 v9, v90, v8
	v_fmac_f32_e32 v69, v90, v68
	v_fmac_f32_e32 v9, v77, v68
	v_fmac_f32_e32 v69, v91, v8
	v_cvt_pk_bf16_f32 v136, v8, v68
	ds_write_b32 v146, v136 offset:2304
	v_fmac_f32_e32 v10, v90, v9
	v_fmac_f32_e32 v70, v90, v69
	v_fmac_f32_e32 v10, v77, v69
	v_fmac_f32_e32 v70, v91, v9
	v_cvt_pk_bf16_f32 v137, v9, v69
	ds_write_b32 v146, v137 offset:2592
	v_fmac_f32_e32 v11, v90, v10
	v_fmac_f32_e32 v71, v90, v70
	v_fmac_f32_e32 v11, v77, v70
	v_fmac_f32_e32 v71, v91, v10
	v_cvt_pk_bf16_f32 v138, v10, v70
	ds_write_b32 v146, v138 offset:2880
	s_waitcnt lgkmcnt(11)
; __device__ __forceinline__ unsigned cvt_pk_bf16(float lo, float hi) { unsigned r; asm volatile("v_cvt_pk_bf16_f32 %0, %1, %2" : "=v"(r) : "v"(lo), "v"(hi)); return r; }
; #define LAS __attribute__((address_space(3)))
; __device__ __forceinline__ float gelu_tanh(float x) { const float z = 0.7978845608028654f * (x + 0.044715f * x * x * x); const float e = __builtin_amdgcn_exp2f(2.f * LOG2E * z); return 0.5f * x * (2.f - 2.f * __builtin_amdgcn_rcpf(1.f + e)); }
; __device__ __forceinline__ void ssm_pass2(LAS unsigned char* lds, const bf16_t* US, const float* SST, bf16_t* YB, const float* ABAR, const bf16_t* BBH, const bf16_t* BBL, const bf16_t* CMH, const bf16_t* CML, const float* dco, int gw, int NGW, int lane, int wave) {
;     ...
;             for (int t = 0; t < 16; ++t) { const float nr = S.ar * xr - S.ai * xi + br[t], ni = S.ar * xi + S.ai * xr + bi[t]; xr = nr; xi = ni; br[t] = xr; bi[t] = xi; }
; #pragma unroll
;             for (int t = 0; t < 16; ++t) { tile[t * TSTR + lane] = br[t]; tile[t * TSTR + 64 + lane] = bi[t]; }
;             asm volatile("s_waitcnt lgkmcnt(0)" ::: "memory");
;             f32x4 acc = {0.f, 0.f, 0.f, 0.f}, acc2 = {0.f, 0.f, 0.f, 0.f};
;             f32x4 xa[4][2];
; #pragma unroll
;             for (int ks = 0; ks < 4; ++ks) { xa[ks][0] = *(const LAS f32x4*)(tile + fr * TSTR + ks * 32 + fq * 8); xa[ks][1] = *(const LAS f32x4*)(tile + fr * TSTR + ks * 32 + fq * 8 + 4); }
; #pragma unroll
;             for (int ks = 0; ks < 4; ++ks) { const f32x4 x0 = xa[ks][0], x1 = xa[ks][1]; u32x4 h;
;                 h.x = cvt_pk_bf16(x0[0], x0[1]); h.y = cvt_pk_bf16(x0[2], x0[3]); h.z = cvt_pk_bf16(x1[0], x1[1]); h.w = cvt_pk_bf16(x1[2], x1[3]);
;                 const bf16x8 xh = __builtin_bit_cast(bf16x8, h);
;                 if (ks & 1) acc2 = __builtin_amdgcn_mfma_f32_16x16x32_bf16(xh, ch[ks], acc2, 0, 0, 0); else acc = __builtin_amdgcn_mfma_f32_16x16x32_bf16(xh, ch[ks], acc, 0, 0, 0); }
;             acc = acc + acc2;
; #pragma unroll
;             for (int i = 0; i < 4; ++i) { const float y = acc[i] + dh * ud[i];
;                 const unsigned w = cvt_pk_bf16(gelu_tanh(y), 0.f); YB[(size_t)(tok + 4 * fq + i) * SSMW + g * 16 + fr] = (bf16_t)(w & 0xffffu); }
;             asm volatile("s_waitcnt lgkmcnt(0)" ::: "memory");
	v_fmac_f32_e32 v12, v90, v11
	v_fmac_f32_e32 v72, v90, v71
	v_fmac_f32_e32 v12, v77, v71
	v_fmac_f32_e32 v72, v91, v11
	v_cvt_pk_bf16_f32 v139, v11, v71
	ds_write_b32 v146, v139 offset:3168
	v_fmac_f32_e32 v13, v90, v12
	v_fmac_f32_e32 v73, v90, v72
	v_fmac_f32_e32 v13, v77, v72
	v_fmac_f32_e32 v73, v91, v12
	v_cvt_pk_bf16_f32 v140, v12, v72
	ds_write_b32 v146, v140 offset:3456
	v_fmac_f32_e32 v14, v90, v13
	v_fmac_f32_e32 v74, v90, v73
	v_fmac_f32_e32 v14, v77, v73
	v_fmac_f32_e32 v74, v91, v13
	v_cvt_pk_bf16_f32 v141, v13, v73
	ds_write_b32 v146, v141 offset:3744
	v_fmac_f32_e32 v15, v90, v14
	v_fmac_f32_e32 v75, v90, v74
	v_fmac_f32_e32 v15, v77, v74
	v_fmac_f32_e32 v75, v91, v14
	v_cvt_pk_bf16_f32 v142, v14, v74
	ds_write_b32 v146, v142 offset:4032
	v_cvt_pk_bf16_f32 v143, v15, v75
	ds_write_b32 v146, v143 offset:4320
	v_mov_b32_e32 v100, v15
	v_mov_b32_e32 v76, v75
	s_waitcnt lgkmcnt(0)
	ds_read_b128 v[198:201], v147
	ds_read_b128 v[202:205], v147 offset:64
	ds_read_b128 v[206:209], v147 offset:128
	ds_read_b128 v[210:213], v147 offset:192
	s_waitcnt lgkmcnt(3)
	v_mfma_f32_16x16x32_bf16 v[92:95], v[198:201], v[214:217], 0
	s_waitcnt lgkmcnt(2)
	v_mfma_f32_16x16x32_bf16 v[96:99], v[202:205], v[218:221], 0
	s_waitcnt lgkmcnt(1)
	v_mfma_f32_16x16x32_bf16 v[92:95], v[206:209], v[222:225], v[92:95]
	s_waitcnt lgkmcnt(0)
	v_mfma_f32_16x16x32_bf16 v[96:99], v[210:213], v[226:229], v[96:99]
	s_add_i32 s20, s20, 1
	s_nop 7
	v_pk_add_f32 v[92:93], v[92:93], v[96:97]
	v_fma_f32 v92, v124, v156, v92
	v_mul_f32_e32 v101, 0x3d372713, v92
	v_pk_add_f32 v[94:95], v[94:95], v[98:99]
	v_fmac_f32_e32 v93, v124, v157
	v_mul_f32_e32 v101, v92, v101
	v_fma_f32 v94, v124, v158, v94
	v_mul_f32_e32 v102, 0.5, v92
	v_mul_f32_e32 v103, 0x3d372713, v93
	v_fma_f32 v92, v92, v101, v92
	v_fmac_f32_e32 v95, v124, v159
	v_mul_f32_e32 v105, 0x3d372713, v94
	v_mul_f32_e32 v103, v93, v103
	v_mul_f32_e32 v92, 0x3f4c422a, v92
	v_mul_f32_e32 v104, 0.5, v93
	v_mul_f32_e32 v107, 0x3d372713, v95
	v_mul_f32_e32 v105, v94, v105
	v_fma_f32 v93, v93, v103, v93
	v_mul_f32_e32 v92, 0x4038aa3b, v92
	v_mul_f32_e32 v106, 0.5, v94
	v_mul_f32_e32 v107, v95, v107
	v_fma_f32 v94, v94, v105, v94
	v_mul_f32_e32 v93, 0x3f4c422a, v93
	v_exp_f32_e32 v92, v92
	v_mul_f32_e32 v108, 0.5, v95
	v_fma_f32 v95, v95, v107, v95
	v_mul_f32_e32 v94, 0x3f4c422a, v94
	v_mul_f32_e32 v93, 0x4038aa3b, v93
	v_mul_f32_e32 v95, 0x3f4c422a, v95
	v_mul_f32_e32 v94, 0x4038aa3b, v94
	v_exp_f32_e32 v93, v93
	v_mul_f32_e32 v95, 0x4038aa3b, v95
	v_exp_f32_e32 v94, v94
	v_exp_f32_e32 v95, v95
	v_add_f32_e32 v92, 1.0, v92
	v_rcp_f32_e32 v92, v92
	v_add_f32_e32 v93, 1.0, v93
	v_add_f32_e32 v94, 1.0, v94
	v_rcp_f32_e32 v93, v93
	v_add_f32_e32 v95, 1.0, v95
	v_rcp_f32_e32 v94, v94
	v_rcp_f32_e32 v95, v95
	v_fma_f32 v92, v92, -2.0, 2.0
	v_mul_f32_e32 v92, v102, v92
	v_fma_f32 v93, v93, -2.0, 2.0
	v_cvt_pk_bf16_f32 v92, v92, v81
	v_fma_f32 v94, v94, -2.0, 2.0
	v_mul_f32_e32 v93, v104, v93
	global_store_short v[150:151], v92, off
	v_cvt_pk_bf16_f32 v92, v93, v81
	v_fma_f32 v95, v95, -2.0, 2.0
	v_mul_f32_e32 v94, v106, v94
	global_store_short v[150:151], v92, off offset:1024
	v_cvt_pk_bf16_f32 v92, v94, v81
	v_mul_f32_e32 v95, v108, v95
	global_store_short v[150:151], v92, off offset:2048
	v_cvt_pk_bf16_f32 v92, v95, v81
	global_store_short v[150:151], v92, off offset:3072
	v_lshl_add_u64 v[150:151], v[150:151], 0, s[100:101]
	s_cmp_eq_u32 s20, 16
	s_waitcnt vmcnt(4)
	s_cbranch_scc0 .Lssm2_grp
	s_add_i32 s70, s70, s33
	s_add_i32 s68, s68, s69
	s_cmpk_gt_i32 s70, 0xfff
	s_cbranch_scc0 .LBB0_547
